# prologue w_in transpose: 32 row loads per item issued back to back (was load-wait-write one dword at a time), on top of m3 tail + attention loop changes
# speedup vs baseline: 1.0637x; 1.0139x over previous
.LBB0_58:
	v_mov_b32_e32 v44, 0
	v_mov_b32_e32 v45, 0
	v_mov_b32_e32 v46, 0
	v_mov_b32_e32 v47, 0
	v_mov_b32_e32 v48, 0
	v_mov_b32_e32 v49, 0
	v_mov_b32_e32 v50, 0
	v_mov_b32_e32 v51, 0
	v_mov_b32_e32 v52, 0
	v_mov_b32_e32 v53, 0
	v_mov_b32_e32 v54, 0
	v_mov_b32_e32 v55, 0
	v_mov_b32_e32 v56, 0
	v_mov_b32_e32 v57, 0
	v_mov_b32_e32 v58, 0
	v_mov_b32_e32 v59, 0
	v_mov_b32_e32 v60, 0
	v_mov_b32_e32 v61, 0
	v_mov_b32_e32 v62, 0
	v_mov_b32_e32 v63, 0
	v_mov_b32_e32 v64, 0
	v_mov_b32_e32 v65, 0
	v_mov_b32_e32 v66, 0
	v_mov_b32_e32 v67, 0
	v_mov_b32_e32 v68, 0
	v_mov_b32_e32 v69, 0
	v_mov_b32_e32 v70, 0
	v_mov_b32_e32 v71, 0
	v_mov_b32_e32 v72, 0
	v_mov_b32_e32 v73, 0
	v_mov_b32_e32 v74, 0
	v_mov_b32_e32 v75, 0
	s_and_saveexec_b64 s[16:17], s[10:11]
	v_lshl_add_u64 v[42:43], v[26:27], 0, s[12:13]
	global_load_dword v44, v[42:43], off
	v_lshl_add_u64 v[42:43], v[24:25], 0, s[12:13]
	global_load_dword v45, v[42:43], off
	v_lshl_add_u64 v[42:43], v[22:23], 0, s[12:13]
	global_load_dword v46, v[42:43], off
	v_lshl_add_u64 v[42:43], v[20:21], 0, s[12:13]
	global_load_dword v47, v[42:43], off
	v_lshl_add_u64 v[42:43], v[18:19], 0, s[12:13]
	global_load_dword v48, v[42:43], off
	v_lshl_add_u64 v[42:43], v[16:17], 0, s[12:13]
	global_load_dword v49, v[42:43], off
	v_lshl_add_u64 v[42:43], v[14:15], 0, s[12:13]
	global_load_dword v50, v[42:43], off
	v_lshl_add_u64 v[42:43], v[12:13], 0, s[12:13]
	global_load_dword v51, v[42:43], off
	s_add_u32 s12, s12, 0xa0400
	s_addc_u32 s13, s13, 0
	v_lshl_add_u64 v[42:43], v[26:27], 0, s[12:13]
	global_load_dword v52, v[42:43], off
	v_lshl_add_u64 v[42:43], v[24:25], 0, s[12:13]
	global_load_dword v53, v[42:43], off
	v_lshl_add_u64 v[42:43], v[22:23], 0, s[12:13]
	global_load_dword v54, v[42:43], off
	v_lshl_add_u64 v[42:43], v[20:21], 0, s[12:13]
	global_load_dword v55, v[42:43], off
	v_lshl_add_u64 v[42:43], v[18:19], 0, s[12:13]
	global_load_dword v56, v[42:43], off
	v_lshl_add_u64 v[42:43], v[16:17], 0, s[12:13]
	global_load_dword v57, v[42:43], off
	v_lshl_add_u64 v[42:43], v[14:15], 0, s[12:13]
	global_load_dword v58, v[42:43], off
	v_lshl_add_u64 v[42:43], v[12:13], 0, s[12:13]
	global_load_dword v59, v[42:43], off
	s_add_u32 s12, s12, 0xa0400
	s_addc_u32 s13, s13, 0
	v_lshl_add_u64 v[42:43], v[26:27], 0, s[12:13]
	global_load_dword v60, v[42:43], off
	v_lshl_add_u64 v[42:43], v[24:25], 0, s[12:13]
	global_load_dword v61, v[42:43], off
	v_lshl_add_u64 v[42:43], v[22:23], 0, s[12:13]
	global_load_dword v62, v[42:43], off
	v_lshl_add_u64 v[42:43], v[20:21], 0, s[12:13]
	global_load_dword v63, v[42:43], off
	v_lshl_add_u64 v[42:43], v[18:19], 0, s[12:13]
	global_load_dword v64, v[42:43], off
	v_lshl_add_u64 v[42:43], v[16:17], 0, s[12:13]
	global_load_dword v65, v[42:43], off
	v_lshl_add_u64 v[42:43], v[14:15], 0, s[12:13]
	global_load_dword v66, v[42:43], off
	v_lshl_add_u64 v[42:43], v[12:13], 0, s[12:13]
	global_load_dword v67, v[42:43], off
	s_add_u32 s12, s12, 0xa0400
	s_addc_u32 s13, s13, 0
	v_lshl_add_u64 v[42:43], v[26:27], 0, s[12:13]
	global_load_dword v68, v[42:43], off
	v_lshl_add_u64 v[42:43], v[24:25], 0, s[12:13]
	global_load_dword v69, v[42:43], off
	v_lshl_add_u64 v[42:43], v[22:23], 0, s[12:13]
	global_load_dword v70, v[42:43], off
	v_lshl_add_u64 v[42:43], v[20:21], 0, s[12:13]
	global_load_dword v71, v[42:43], off
	v_lshl_add_u64 v[42:43], v[18:19], 0, s[12:13]
	global_load_dword v72, v[42:43], off
	v_lshl_add_u64 v[42:43], v[16:17], 0, s[12:13]
	global_load_dword v73, v[42:43], off
	v_lshl_add_u64 v[42:43], v[14:15], 0, s[12:13]
	global_load_dword v74, v[42:43], off
	v_lshl_add_u64 v[42:43], v[12:13], 0, s[12:13]
	global_load_dword v75, v[42:43], off
	s_or_b64 exec, exec, s[16:17]
	s_waitcnt vmcnt(0)
	ds_write_b32 v6, v44
	ds_write_b32 v6, v45 offset:264
	ds_write_b32 v6, v46 offset:528
	ds_write_b32 v6, v47 offset:792
	ds_write_b32 v6, v48 offset:1056
	ds_write_b32 v6, v49 offset:1320
	ds_write_b32 v6, v50 offset:1584
	ds_write_b32 v6, v51 offset:1848
	v_add_u32_e32 v6, 0x840, v6
	ds_write_b32 v6, v52
	ds_write_b32 v6, v53 offset:264
	ds_write_b32 v6, v54 offset:528
	ds_write_b32 v6, v55 offset:792
	ds_write_b32 v6, v56 offset:1056
	ds_write_b32 v6, v57 offset:1320
	ds_write_b32 v6, v58 offset:1584
	ds_write_b32 v6, v59 offset:1848
	v_add_u32_e32 v6, 0x840, v6
	ds_write_b32 v6, v60
	ds_write_b32 v6, v61 offset:264
	ds_write_b32 v6, v62 offset:528
	ds_write_b32 v6, v63 offset:792
	ds_write_b32 v6, v64 offset:1056
	ds_write_b32 v6, v65 offset:1320
	ds_write_b32 v6, v66 offset:1584
	ds_write_b32 v6, v67 offset:1848
	v_add_u32_e32 v6, 0x840, v6
	ds_write_b32 v6, v68
	ds_write_b32 v6, v69 offset:264
	ds_write_b32 v6, v70 offset:528
	ds_write_b32 v6, v71 offset:792
	ds_write_b32 v6, v72 offset:1056
	ds_write_b32 v6, v73 offset:1320
	ds_write_b32 v6, v74 offset:1584
	ds_write_b32 v6, v75 offset:1848
	s_branch .LBB0_17
